# SwiGLU GEMM epilogue hand-scheduled: 4 independent sigmoid chains interleaved, no trans-hazard nops, saddr stores with immediate offsets
# speedup vs baseline: 1.0033x; 1.0033x over previous
; DI unsigned cvt_pk_bf16(float lo, float hi) { unsigned r; asm volatile("v_cvt_pk_bf16_f32 %0, %1, %2" : "=v"(r) : "v"(lo), "v"(hi)); return r; }
; DI float sigmoidf_(float x) { return __builtin_amdgcn_rcpf(1.f + __expf(-x)); }
;     DI void operator()(const Acc& acc, const Unit& u, int wr, int wc, int fr, int fq) const {
;         asm volatile("" : "+v"(fr), "+v"(fq));
; #pragma unroll
;         for (int ai = 0; ai < 2; ++ai)
; #pragma unroll
;             for (int m = 0; m < 4; ++m) { const int row = u.pm * 256 + ai * 128 + wr * 64 + m * 16 + fr;
; #pragma unroll
;                 for (int bj = 0; bj < 2; ++bj) { const int j0 = u.pn * 128 + bj * 64 + wc * 16 + 4 * fq; const f32x4 v0 = acc[ai][bj][m][0], v1 = acc[ai][bj][m][1];
;                     const float h0 = v0[0] * sigmoidf_(v0[0]) * v0[1], h1 = v0[2] * sigmoidf_(v0[2]) * v0[3], h2 = v1[0] * sigmoidf_(v1[0]) * v1[1], h3 = v1[2] * sigmoidf_(v1[2]) * v1[3];
;                     u32x2 w; w.x = cvt_pk_bf16(h0, h1); w.y = cvt_pk_bf16(h2, h3);
;                     *(u32x2*)(H + (size_t)(j0 >> 6) * NT * 64 + (size_t)row * 64 + (j0 & 63)) = w; }
;                 asm volatile("" ::: "memory"); }
.LBB0_138:
	s_lshl_b32 s2, s84, 8
	s_add_i32 s2, s2, s73
	v_add_u32_e32 v195, s2, v1
	s_lshl_b32 s2, s66, 7
	s_or_b32 s2, s2, s78
	v_lshl_add_u32 v196, v131, 2, s2
	s_mov_b32 s15, 0x208000
	v_ashrrev_i32_e32 v197, 6, v196
	v_mul_lo_u32 v197, v197, s15
	v_and_b32_e32 v196, 60, v196
	v_lshl_add_u32 v194, v195, 7, v197
	v_lshl_add_u32 v194, v196, 1, v194
	v_mul_f32_e32 v184, 0xbfb8aa3b, v126
	v_mul_f32_e32 v185, 0xbfb8aa3b, v128
	v_mul_f32_e32 v186, 0xbfb8aa3b, v122
	v_mul_f32_e32 v187, 0xbfb8aa3b, v124
	v_exp_f32_e32 v184, v184
	v_exp_f32_e32 v185, v185
	v_exp_f32_e32 v186, v186
	v_exp_f32_e32 v187, v187
	v_add_f32_e32 v184, 1.0, v184
	v_add_f32_e32 v185, 1.0, v185
	v_add_f32_e32 v186, 1.0, v186
	v_add_f32_e32 v187, 1.0, v187
	v_rcp_f32_e32 v184, v184
	v_rcp_f32_e32 v185, v185
	v_rcp_f32_e32 v186, v186
	v_rcp_f32_e32 v187, v187
	v_mul_f32_e32 v188, 0xbfb8aa3b, v118
	v_mul_f32_e32 v189, 0xbfb8aa3b, v120
	v_mul_f32_e32 v190, 0xbfb8aa3b, v114
	v_mul_f32_e32 v191, 0xbfb8aa3b, v116
	v_mul_f32_e32 v126, v126, v184
	v_mul_f32_e32 v128, v128, v185
	v_mul_f32_e32 v122, v122, v186
	v_mul_f32_e32 v124, v124, v187
	v_exp_f32_e32 v188, v188
	v_exp_f32_e32 v189, v189
	v_exp_f32_e32 v190, v190
	v_exp_f32_e32 v191, v191
	v_mul_f32_e32 v126, v127, v126
	v_mul_f32_e32 v128, v129, v128
	v_mul_f32_e32 v122, v123, v122
	v_mul_f32_e32 v124, v125, v124
	v_add_f32_e32 v188, 1.0, v188
	v_add_f32_e32 v189, 1.0, v189
	v_add_f32_e32 v190, 1.0, v190
	v_add_f32_e32 v191, 1.0, v191
	v_cvt_pk_bf16_f32 v126, v126, v128
	v_cvt_pk_bf16_f32 v127, v122, v124
	v_mov_b32_e32 v192, v194
	global_store_dwordx2 v192, v[126:127], s[20:21]
	v_rcp_f32_e32 v188, v188
	v_rcp_f32_e32 v189, v189
	v_rcp_f32_e32 v190, v190
	v_rcp_f32_e32 v191, v191
	v_mul_f32_e32 v184, 0xbfb8aa3b, v110
	v_mul_f32_e32 v185, 0xbfb8aa3b, v112
	v_mul_f32_e32 v186, 0xbfb8aa3b, v106
	v_mul_f32_e32 v187, 0xbfb8aa3b, v108
	v_mul_f32_e32 v118, v118, v188
	v_mul_f32_e32 v120, v120, v189
	v_mul_f32_e32 v114, v114, v190
	v_mul_f32_e32 v116, v116, v191
	v_exp_f32_e32 v184, v184
	v_exp_f32_e32 v185, v185
	v_exp_f32_e32 v186, v186
	v_exp_f32_e32 v187, v187
	v_mul_f32_e32 v118, v119, v118
	v_mul_f32_e32 v120, v121, v120
	v_mul_f32_e32 v114, v115, v114
	v_mul_f32_e32 v116, v117, v116
	v_add_f32_e32 v184, 1.0, v184
	v_add_f32_e32 v185, 1.0, v185
	v_add_f32_e32 v186, 1.0, v186
	v_add_f32_e32 v187, 1.0, v187
	v_cvt_pk_bf16_f32 v118, v118, v120
	v_cvt_pk_bf16_f32 v119, v114, v116
	v_add_u32_e32 v193, 0x208000, v194
	global_store_dwordx2 v193, v[118:119], s[20:21]
	v_rcp_f32_e32 v184, v184
	v_rcp_f32_e32 v185, v185
	v_rcp_f32_e32 v186, v186
	v_rcp_f32_e32 v187, v187
	v_mul_f32_e32 v188, 0xbfb8aa3b, v102
	v_mul_f32_e32 v189, 0xbfb8aa3b, v104
	v_mul_f32_e32 v190, 0xbfb8aa3b, v98
	v_mul_f32_e32 v191, 0xbfb8aa3b, v100
	v_mul_f32_e32 v110, v110, v184
	v_mul_f32_e32 v112, v112, v185
	v_mul_f32_e32 v106, v106, v186
	v_mul_f32_e32 v108, v108, v187
	v_exp_f32_e32 v188, v188
	v_exp_f32_e32 v189, v189
	v_exp_f32_e32 v190, v190
	v_exp_f32_e32 v191, v191
	v_mul_f32_e32 v110, v111, v110
	v_mul_f32_e32 v112, v113, v112
	v_mul_f32_e32 v106, v107, v106
	v_mul_f32_e32 v108, v109, v108
	v_add_f32_e32 v188, 1.0, v188
	v_add_f32_e32 v189, 1.0, v189
	v_add_f32_e32 v190, 1.0, v190
	v_add_f32_e32 v191, 1.0, v191
	v_cvt_pk_bf16_f32 v110, v110, v112
	v_cvt_pk_bf16_f32 v111, v106, v108
	v_mov_b32_e32 v192, v194
	global_store_dwordx2 v192, v[110:111], s[20:21] offset:2048
	v_rcp_f32_e32 v188, v188
	v_rcp_f32_e32 v189, v189
	v_rcp_f32_e32 v190, v190
	v_rcp_f32_e32 v191, v191
	v_mul_f32_e32 v184, 0xbfb8aa3b, v94
	v_mul_f32_e32 v185, 0xbfb8aa3b, v96
	v_mul_f32_e32 v186, 0xbfb8aa3b, v90
	v_mul_f32_e32 v187, 0xbfb8aa3b, v92
	v_mul_f32_e32 v102, v102, v188
	v_mul_f32_e32 v104, v104, v189
	v_mul_f32_e32 v98, v98, v190
	v_mul_f32_e32 v100, v100, v191
	v_exp_f32_e32 v184, v184
	v_exp_f32_e32 v185, v185
	v_exp_f32_e32 v186, v186
	v_exp_f32_e32 v187, v187
	v_mul_f32_e32 v102, v103, v102
	v_mul_f32_e32 v104, v105, v104
	v_mul_f32_e32 v98, v99, v98
	v_mul_f32_e32 v100, v101, v100
	v_add_f32_e32 v184, 1.0, v184
	v_add_f32_e32 v185, 1.0, v185
	v_add_f32_e32 v186, 1.0, v186
	v_add_f32_e32 v187, 1.0, v187
	v_cvt_pk_bf16_f32 v102, v102, v104
	v_cvt_pk_bf16_f32 v103, v98, v100
	v_add_u32_e32 v193, 0x208000, v194
	global_store_dwordx2 v193, v[102:103], s[20:21] offset:2048
	v_rcp_f32_e32 v184, v184
	v_rcp_f32_e32 v185, v185
	v_rcp_f32_e32 v186, v186
	v_rcp_f32_e32 v187, v187
	v_mul_f32_e32 v188, 0xbfb8aa3b, v86
	v_mul_f32_e32 v189, 0xbfb8aa3b, v88
	v_mul_f32_e32 v190, 0xbfb8aa3b, v82
	v_mul_f32_e32 v191, 0xbfb8aa3b, v84
	v_mul_f32_e32 v94, v94, v184
	v_mul_f32_e32 v96, v96, v185
	v_mul_f32_e32 v90, v90, v186
	v_mul_f32_e32 v92, v92, v187
	v_exp_f32_e32 v188, v188
	v_exp_f32_e32 v189, v189
	v_exp_f32_e32 v190, v190
	v_exp_f32_e32 v191, v191
	v_mul_f32_e32 v94, v95, v94
	v_mul_f32_e32 v96, v97, v96
	v_mul_f32_e32 v90, v91, v90
	v_mul_f32_e32 v92, v93, v92
	v_add_f32_e32 v188, 1.0, v188
	v_add_f32_e32 v189, 1.0, v189
	v_add_f32_e32 v190, 1.0, v190
	v_add_f32_e32 v191, 1.0, v191
	v_cvt_pk_bf16_f32 v94, v94, v96
	v_cvt_pk_bf16_f32 v95, v90, v92
	v_add_u32_e32 v192, 0x1000, v194
	global_store_dwordx2 v192, v[94:95], s[20:21]
	v_rcp_f32_e32 v188, v188
	v_rcp_f32_e32 v189, v189
	v_rcp_f32_e32 v190, v190
	v_rcp_f32_e32 v191, v191
	v_mul_f32_e32 v184, 0xbfb8aa3b, v78
	v_mul_f32_e32 v185, 0xbfb8aa3b, v80
	v_mul_f32_e32 v186, 0xbfb8aa3b, v74
	v_mul_f32_e32 v187, 0xbfb8aa3b, v76
	v_mul_f32_e32 v86, v86, v188
	v_mul_f32_e32 v88, v88, v189
	v_mul_f32_e32 v82, v82, v190
	v_mul_f32_e32 v84, v84, v191
	v_exp_f32_e32 v184, v184
	v_exp_f32_e32 v185, v185
	v_exp_f32_e32 v186, v186
; DI unsigned cvt_pk_bf16(float lo, float hi) { unsigned r; asm volatile("v_cvt_pk_bf16_f32 %0, %1, %2" : "=v"(r) : "v"(lo), "v"(hi)); return r; }
; DI float sigmoidf_(float x) { return __builtin_amdgcn_rcpf(1.f + __expf(-x)); }
;     DI void operator()(const Acc& acc, const Unit& u, int wr, int wc, int fr, int fq) const {
;     ...
;             for (int m = 0; m < 4; ++m) { const int row = u.pm * 256 + ai * 128 + wr * 64 + m * 16 + fr;
; #pragma unroll
;                 for (int bj = 0; bj < 2; ++bj) { const int j0 = u.pn * 128 + bj * 64 + wc * 16 + 4 * fq; const f32x4 v0 = acc[ai][bj][m][0], v1 = acc[ai][bj][m][1];
;                     const float h0 = v0[0] * sigmoidf_(v0[0]) * v0[1], h1 = v0[2] * sigmoidf_(v0[2]) * v0[3], h2 = v1[0] * sigmoidf_(v1[0]) * v1[1], h3 = v1[2] * sigmoidf_(v1[2]) * v1[3];
;                     u32x2 w; w.x = cvt_pk_bf16(h0, h1); w.y = cvt_pk_bf16(h2, h3);
;                     *(u32x2*)(H + (size_t)(j0 >> 6) * NT * 64 + (size_t)row * 64 + (j0 & 63)) = w; }
;                 asm volatile("" ::: "memory"); }
	v_exp_f32_e32 v187, v187
	v_mul_f32_e32 v86, v87, v86
	v_mul_f32_e32 v88, v89, v88
	v_mul_f32_e32 v82, v83, v82
	v_mul_f32_e32 v84, v85, v84
	v_add_f32_e32 v184, 1.0, v184
	v_add_f32_e32 v185, 1.0, v185
	v_add_f32_e32 v186, 1.0, v186
	v_add_f32_e32 v187, 1.0, v187
	v_cvt_pk_bf16_f32 v86, v86, v88
	v_cvt_pk_bf16_f32 v87, v82, v84
	v_add_u32_e32 v193, 0x209000, v194
	global_store_dwordx2 v193, v[86:87], s[20:21]
	v_rcp_f32_e32 v184, v184
	v_rcp_f32_e32 v185, v185
	v_rcp_f32_e32 v186, v186
	v_rcp_f32_e32 v187, v187
	v_mul_f32_e32 v188, 0xbfb8aa3b, v70
	v_mul_f32_e32 v189, 0xbfb8aa3b, v72
	v_mul_f32_e32 v190, 0xbfb8aa3b, v66
	v_mul_f32_e32 v191, 0xbfb8aa3b, v68
	v_mul_f32_e32 v78, v78, v184
	v_mul_f32_e32 v80, v80, v185
	v_mul_f32_e32 v74, v74, v186
	v_mul_f32_e32 v76, v76, v187
	v_exp_f32_e32 v188, v188
	v_exp_f32_e32 v189, v189
	v_exp_f32_e32 v190, v190
	v_exp_f32_e32 v191, v191
	v_mul_f32_e32 v78, v79, v78
	v_mul_f32_e32 v80, v81, v80
	v_mul_f32_e32 v74, v75, v74
	v_mul_f32_e32 v76, v77, v76
	v_add_f32_e32 v188, 1.0, v188
	v_add_f32_e32 v189, 1.0, v189
	v_add_f32_e32 v190, 1.0, v190
	v_add_f32_e32 v191, 1.0, v191
	v_cvt_pk_bf16_f32 v78, v78, v80
	v_cvt_pk_bf16_f32 v79, v74, v76
	v_add_u32_e32 v192, 0x1000, v194
	global_store_dwordx2 v192, v[78:79], s[20:21] offset:2048
	v_rcp_f32_e32 v188, v188
	v_rcp_f32_e32 v189, v189
	v_rcp_f32_e32 v190, v190
	v_rcp_f32_e32 v191, v191
	v_mul_f32_e32 v184, 0xbfb8aa3b, v62
	v_mul_f32_e32 v185, 0xbfb8aa3b, v64
	v_mul_f32_e32 v186, 0xbfb8aa3b, v58
	v_mul_f32_e32 v187, 0xbfb8aa3b, v60
	v_mul_f32_e32 v70, v70, v188
	v_mul_f32_e32 v72, v72, v189
	v_mul_f32_e32 v66, v66, v190
	v_mul_f32_e32 v68, v68, v191
	v_exp_f32_e32 v184, v184
	v_exp_f32_e32 v185, v185
	v_exp_f32_e32 v186, v186
	v_exp_f32_e32 v187, v187
	v_mul_f32_e32 v70, v71, v70
	v_mul_f32_e32 v72, v73, v72
	v_mul_f32_e32 v66, v67, v66
	v_mul_f32_e32 v68, v69, v68
	v_add_f32_e32 v184, 1.0, v184
	v_add_f32_e32 v185, 1.0, v185
	v_add_f32_e32 v186, 1.0, v186
	v_add_f32_e32 v187, 1.0, v187
	v_cvt_pk_bf16_f32 v70, v70, v72
	v_cvt_pk_bf16_f32 v71, v66, v68
	v_add_u32_e32 v193, 0x209000, v194
	global_store_dwordx2 v193, v[70:71], s[20:21] offset:2048
	v_rcp_f32_e32 v184, v184
	v_rcp_f32_e32 v185, v185
	v_rcp_f32_e32 v186, v186
	v_rcp_f32_e32 v187, v187
	v_mul_f32_e32 v188, 0xbfb8aa3b, v54
	v_mul_f32_e32 v189, 0xbfb8aa3b, v56
	v_mul_f32_e32 v190, 0xbfb8aa3b, v50
	v_mul_f32_e32 v191, 0xbfb8aa3b, v52
	v_mul_f32_e32 v62, v62, v184
	v_mul_f32_e32 v64, v64, v185
	v_mul_f32_e32 v58, v58, v186
	v_mul_f32_e32 v60, v60, v187
	v_exp_f32_e32 v188, v188
	v_exp_f32_e32 v189, v189
	v_exp_f32_e32 v190, v190
	v_exp_f32_e32 v191, v191
	v_mul_f32_e32 v62, v63, v62
	v_mul_f32_e32 v64, v65, v64
	v_mul_f32_e32 v58, v59, v58
	v_mul_f32_e32 v60, v61, v60
	v_add_f32_e32 v188, 1.0, v188
	v_add_f32_e32 v189, 1.0, v189
	v_add_f32_e32 v190, 1.0, v190
	v_add_f32_e32 v191, 1.0, v191
	v_cvt_pk_bf16_f32 v62, v62, v64
	v_cvt_pk_bf16_f32 v63, v58, v60
	v_add_u32_e32 v192, 0x4000, v194
	global_store_dwordx2 v192, v[62:63], s[20:21]
	v_rcp_f32_e32 v188, v188
	v_rcp_f32_e32 v189, v189
	v_rcp_f32_e32 v190, v190
	v_rcp_f32_e32 v191, v191
	v_mul_f32_e32 v184, 0xbfb8aa3b, v46
	v_mul_f32_e32 v185, 0xbfb8aa3b, v48
	v_mul_f32_e32 v186, 0xbfb8aa3b, v42
	v_mul_f32_e32 v187, 0xbfb8aa3b, v44
	v_mul_f32_e32 v54, v54, v188
	v_mul_f32_e32 v56, v56, v189
	v_mul_f32_e32 v50, v50, v190
	v_mul_f32_e32 v52, v52, v191
	v_exp_f32_e32 v184, v184
	v_exp_f32_e32 v185, v185
	v_exp_f32_e32 v186, v186
	v_exp_f32_e32 v187, v187
	v_mul_f32_e32 v54, v55, v54
	v_mul_f32_e32 v56, v57, v56
	v_mul_f32_e32 v50, v51, v50
	v_mul_f32_e32 v52, v53, v52
	v_add_f32_e32 v184, 1.0, v184
	v_add_f32_e32 v185, 1.0, v185
	v_add_f32_e32 v186, 1.0, v186
	v_add_f32_e32 v187, 1.0, v187
	v_cvt_pk_bf16_f32 v54, v54, v56
	v_cvt_pk_bf16_f32 v55, v50, v52
	v_add_u32_e32 v193, 0x20c000, v194
	global_store_dwordx2 v193, v[54:55], s[20:21]
	v_rcp_f32_e32 v184, v184
	v_rcp_f32_e32 v185, v185
	v_rcp_f32_e32 v186, v186
	v_rcp_f32_e32 v187, v187
	v_mul_f32_e32 v188, 0xbfb8aa3b, v38
	v_mul_f32_e32 v189, 0xbfb8aa3b, v40
	v_mul_f32_e32 v190, 0xbfb8aa3b, v34
	v_mul_f32_e32 v191, 0xbfb8aa3b, v36
	v_mul_f32_e32 v46, v46, v184
	v_mul_f32_e32 v48, v48, v185
	v_mul_f32_e32 v42, v42, v186
	v_mul_f32_e32 v44, v44, v187
	v_exp_f32_e32 v188, v188
	v_exp_f32_e32 v189, v189
	v_exp_f32_e32 v190, v190
	v_exp_f32_e32 v191, v191
	v_mul_f32_e32 v46, v47, v46
	v_mul_f32_e32 v48, v49, v48
	v_mul_f32_e32 v42, v43, v42
; DI unsigned cvt_pk_bf16(float lo, float hi) { unsigned r; asm volatile("v_cvt_pk_bf16_f32 %0, %1, %2" : "=v"(r) : "v"(lo), "v"(hi)); return r; }
; DI float sigmoidf_(float x) { return __builtin_amdgcn_rcpf(1.f + __expf(-x)); }
; #define PG8_BAR __builtin_amdgcn_s_barrier()
; template <class Epi>
; DI void gemm_phase(LAS unsigned char* lds, const Gemm g, const StaticOrder& S, const Epi& E) {
;     ...
;         if (!has_next) break;
; #pragma unroll
;         for (int a = 0; a < 2; ++a)
; #pragma unroll
;             for (int b = 0; b < 2; ++b)
; #pragma unroll
;                 for (int m = 0; m < 4; ++m)
; #pragma unroll
;                     for (int n = 0; n < 2; ++n) acc[a][b][m][n] = (f32x4){0.f, 0.f, 0.f, 0.f};
;         cur = nxt; cA = nA; cB = nB; ++ui;
;         if (wr == 1) PG8_BAR;
;     DI void operator()(const Acc& acc, const Unit& u, int wr, int wc, int fr, int fq) const {
;     ...
;             for (int m = 0; m < 4; ++m) { const int row = u.pm * 256 + ai * 128 + wr * 64 + m * 16 + fr;
; #pragma unroll
;                 for (int bj = 0; bj < 2; ++bj) { const int j0 = u.pn * 128 + bj * 64 + wc * 16 + 4 * fq; const f32x4 v0 = acc[ai][bj][m][0], v1 = acc[ai][bj][m][1];
;                     const float h0 = v0[0] * sigmoidf_(v0[0]) * v0[1], h1 = v0[2] * sigmoidf_(v0[2]) * v0[3], h2 = v1[0] * sigmoidf_(v1[0]) * v1[1], h3 = v1[2] * sigmoidf_(v1[2]) * v1[3];
;                     u32x2 w; w.x = cvt_pk_bf16(h0, h1); w.y = cvt_pk_bf16(h2, h3);
;                     *(u32x2*)(H + (size_t)(j0 >> 6) * NT * 64 + (size_t)row * 64 + (j0 & 63)) = w; }
;                 asm volatile("" ::: "memory"); }
	v_mul_f32_e32 v44, v45, v44
	v_add_f32_e32 v188, 1.0, v188
	v_add_f32_e32 v189, 1.0, v189
	v_add_f32_e32 v190, 1.0, v190
	v_add_f32_e32 v191, 1.0, v191
	v_cvt_pk_bf16_f32 v46, v46, v48
	v_cvt_pk_bf16_f32 v47, v42, v44
	v_add_u32_e32 v192, 0x4000, v194
	global_store_dwordx2 v192, v[46:47], s[20:21] offset:2048
	v_rcp_f32_e32 v188, v188
	v_rcp_f32_e32 v189, v189
	v_rcp_f32_e32 v190, v190
	v_rcp_f32_e32 v191, v191
	v_mul_f32_e32 v184, 0xbfb8aa3b, v30
	v_mul_f32_e32 v185, 0xbfb8aa3b, v32
	v_mul_f32_e32 v186, 0xbfb8aa3b, v26
	v_mul_f32_e32 v187, 0xbfb8aa3b, v28
	v_mul_f32_e32 v38, v38, v188
	v_mul_f32_e32 v40, v40, v189
	v_mul_f32_e32 v34, v34, v190
	v_mul_f32_e32 v36, v36, v191
	v_exp_f32_e32 v184, v184
	v_exp_f32_e32 v185, v185
	v_exp_f32_e32 v186, v186
	v_exp_f32_e32 v187, v187
	v_mul_f32_e32 v38, v39, v38
	v_mul_f32_e32 v40, v41, v40
	v_mul_f32_e32 v34, v35, v34
	v_mul_f32_e32 v36, v37, v36
	v_add_f32_e32 v184, 1.0, v184
	v_add_f32_e32 v185, 1.0, v185
	v_add_f32_e32 v186, 1.0, v186
	v_add_f32_e32 v187, 1.0, v187
	v_cvt_pk_bf16_f32 v38, v38, v40
	v_cvt_pk_bf16_f32 v39, v34, v36
	v_add_u32_e32 v193, 0x20c000, v194
	global_store_dwordx2 v193, v[38:39], s[20:21] offset:2048
	v_rcp_f32_e32 v184, v184
	v_rcp_f32_e32 v185, v185
	v_rcp_f32_e32 v186, v186
	v_rcp_f32_e32 v187, v187
	v_mul_f32_e32 v188, 0xbfb8aa3b, v22
	v_mul_f32_e32 v189, 0xbfb8aa3b, v24
	v_mul_f32_e32 v190, 0xbfb8aa3b, v18
	v_mul_f32_e32 v191, 0xbfb8aa3b, v20
	v_mul_f32_e32 v30, v30, v184
	v_mul_f32_e32 v32, v32, v185
	v_mul_f32_e32 v26, v26, v186
	v_mul_f32_e32 v28, v28, v187
	v_exp_f32_e32 v188, v188
	v_exp_f32_e32 v189, v189
	v_exp_f32_e32 v190, v190
	v_exp_f32_e32 v191, v191
	v_mul_f32_e32 v30, v31, v30
	v_mul_f32_e32 v32, v33, v32
	v_mul_f32_e32 v26, v27, v26
	v_mul_f32_e32 v28, v29, v28
	v_add_f32_e32 v188, 1.0, v188
	v_add_f32_e32 v189, 1.0, v189
	v_add_f32_e32 v190, 1.0, v190
	v_add_f32_e32 v191, 1.0, v191
	v_cvt_pk_bf16_f32 v30, v30, v32
	v_cvt_pk_bf16_f32 v31, v26, v28
	v_add_u32_e32 v192, 0x5000, v194
	global_store_dwordx2 v192, v[30:31], s[20:21]
	v_rcp_f32_e32 v188, v188
	v_rcp_f32_e32 v189, v189
	v_rcp_f32_e32 v190, v190
	v_rcp_f32_e32 v191, v191
	v_mul_f32_e32 v184, 0xbfb8aa3b, v14
	v_mul_f32_e32 v185, 0xbfb8aa3b, v16
	v_mul_f32_e32 v186, 0xbfb8aa3b, v10
	v_mul_f32_e32 v187, 0xbfb8aa3b, v12
	v_mul_f32_e32 v22, v22, v188
	v_mul_f32_e32 v24, v24, v189
	v_mul_f32_e32 v18, v18, v190
	v_mul_f32_e32 v20, v20, v191
	v_exp_f32_e32 v184, v184
	v_exp_f32_e32 v185, v185
	v_exp_f32_e32 v186, v186
	v_exp_f32_e32 v187, v187
	v_mul_f32_e32 v22, v23, v22
	v_mul_f32_e32 v24, v25, v24
	v_mul_f32_e32 v18, v19, v18
	v_mul_f32_e32 v20, v21, v20
	v_add_f32_e32 v184, 1.0, v184
	v_add_f32_e32 v185, 1.0, v185
	v_add_f32_e32 v186, 1.0, v186
	v_add_f32_e32 v187, 1.0, v187
	v_cvt_pk_bf16_f32 v22, v22, v24
	v_cvt_pk_bf16_f32 v23, v18, v20
	v_add_u32_e32 v193, 0x20d000, v194
	global_store_dwordx2 v193, v[22:23], s[20:21]
	v_rcp_f32_e32 v184, v184
	v_rcp_f32_e32 v185, v185
	v_rcp_f32_e32 v186, v186
	v_rcp_f32_e32 v187, v187
	v_mul_f32_e32 v188, 0xbfb8aa3b, v6
	v_mul_f32_e32 v189, 0xbfb8aa3b, v8
	v_mul_f32_e32 v190, 0xbfb8aa3b, v2
	v_mul_f32_e32 v191, 0xbfb8aa3b, v4
	v_mul_f32_e32 v14, v14, v184
	v_mul_f32_e32 v16, v16, v185
	v_mul_f32_e32 v10, v10, v186
	v_mul_f32_e32 v12, v12, v187
	v_exp_f32_e32 v188, v188
	v_exp_f32_e32 v189, v189
	v_exp_f32_e32 v190, v190
	v_exp_f32_e32 v191, v191
	v_mul_f32_e32 v14, v15, v14
	v_mul_f32_e32 v16, v17, v16
	v_mul_f32_e32 v10, v11, v10
	v_mul_f32_e32 v12, v13, v12
	v_add_f32_e32 v188, 1.0, v188
	v_add_f32_e32 v189, 1.0, v189
	v_add_f32_e32 v190, 1.0, v190
	v_add_f32_e32 v191, 1.0, v191
	v_cvt_pk_bf16_f32 v14, v14, v16
	v_cvt_pk_bf16_f32 v15, v10, v12
	v_add_u32_e32 v192, 0x5000, v194
	global_store_dwordx2 v192, v[14:15], s[20:21] offset:2048
	v_rcp_f32_e32 v188, v188
	v_rcp_f32_e32 v189, v189
	v_rcp_f32_e32 v190, v190
	v_rcp_f32_e32 v191, v191
	s_nop 0
	v_mul_f32_e32 v6, v6, v188
	v_mul_f32_e32 v8, v8, v189
	v_mul_f32_e32 v2, v2, v190
	v_mul_f32_e32 v4, v4, v191
	v_mul_f32_e32 v6, v7, v6
	v_mul_f32_e32 v8, v9, v8
	v_mul_f32_e32 v2, v3, v2
	v_mul_f32_e32 v4, v5, v4
	v_cvt_pk_bf16_f32 v6, v6, v8
	v_cvt_pk_bf16_f32 v7, v2, v4
	v_add_u32_e32 v193, 0x20d000, v194
	global_store_dwordx2 v193, v[6:7], s[20:21] offset:2048
	s_mov_b64 s[18:19], -1
	s_andn2_b64 vcc, exec, s[38:39]
	s_cbranch_vccnz .LBB0_127
	s_andn2_b64 vcc, exec, s[0:1]
	s_cbranch_vccnz .LBB0_126
	s_barrier
	s_branch .LBB0_126

; DI unsigned cvt_pk_bf16(float lo, float hi) { unsigned r; asm volatile("v_cvt_pk_bf16_f32 %0, %1, %2" : "=v"(r) : "v"(lo), "v"(hi)); return r; }
; DI float sigmoidf_(float x) { return __builtin_amdgcn_rcpf(1.f + __expf(-x)); }
;     DI void operator()(const Acc& acc, const Unit& u, int wr, int wc, int fr, int fq) const {
;         asm volatile("" : "+v"(fr), "+v"(fq));
; #pragma unroll
;         for (int ai = 0; ai < 2; ++ai)
; #pragma unroll
;             for (int m = 0; m < 4; ++m) { const int row = u.pm * 256 + ai * 128 + wr * 64 + m * 16 + fr;
; #pragma unroll
;                 for (int bj = 0; bj < 2; ++bj) { const int j0 = u.pn * 128 + bj * 64 + wc * 16 + 4 * fq; const f32x4 v0 = acc[ai][bj][m][0], v1 = acc[ai][bj][m][1];
;                     const float h0 = v0[0] * sigmoidf_(v0[0]) * v0[1], h1 = v0[2] * sigmoidf_(v0[2]) * v0[3], h2 = v1[0] * sigmoidf_(v1[0]) * v1[1], h3 = v1[2] * sigmoidf_(v1[2]) * v1[3];
;                     u32x2 w; w.x = cvt_pk_bf16(h0, h1); w.y = cvt_pk_bf16(h2, h3);
;                     *(u32x2*)(H + (size_t)(j0 >> 6) * NT * 64 + (size_t)row * 64 + (j0 & 63)) = w; }
;                 asm volatile("" ::: "memory"); }
.LBB0_2165:
	s_lshl_b32 s2, s79, 8
	s_add_i32 s2, s2, s72
	v_add_u32_e32 v195, s2, v1
	s_lshl_b32 s2, s66, 7
	s_or_b32 s2, s2, s75
	v_lshl_add_u32 v196, v147, 2, s2
	s_mov_b32 s15, 0x208000
	v_ashrrev_i32_e32 v197, 6, v196
	v_mul_lo_u32 v197, v197, s15
	v_and_b32_e32 v196, 60, v196
	v_lshl_add_u32 v194, v195, 7, v197
	v_lshl_add_u32 v194, v196, 1, v194
	v_mul_f32_e32 v184, 0xbfb8aa3b, v126
	v_mul_f32_e32 v185, 0xbfb8aa3b, v128
	v_mul_f32_e32 v186, 0xbfb8aa3b, v122
	v_mul_f32_e32 v187, 0xbfb8aa3b, v124
	v_exp_f32_e32 v184, v184
	v_exp_f32_e32 v185, v185
	v_exp_f32_e32 v186, v186
	v_exp_f32_e32 v187, v187
	v_add_f32_e32 v184, 1.0, v184
	v_add_f32_e32 v185, 1.0, v185
	v_add_f32_e32 v186, 1.0, v186
	v_add_f32_e32 v187, 1.0, v187
	v_rcp_f32_e32 v184, v184
	v_rcp_f32_e32 v185, v185
	v_rcp_f32_e32 v186, v186
	v_rcp_f32_e32 v187, v187
	v_mul_f32_e32 v188, 0xbfb8aa3b, v118
	v_mul_f32_e32 v189, 0xbfb8aa3b, v120
	v_mul_f32_e32 v190, 0xbfb8aa3b, v114
	v_mul_f32_e32 v191, 0xbfb8aa3b, v116
	v_mul_f32_e32 v126, v126, v184
	v_mul_f32_e32 v128, v128, v185
	v_mul_f32_e32 v122, v122, v186
	v_mul_f32_e32 v124, v124, v187
	v_exp_f32_e32 v188, v188
	v_exp_f32_e32 v189, v189
	v_exp_f32_e32 v190, v190
	v_exp_f32_e32 v191, v191
	v_mul_f32_e32 v126, v127, v126
	v_mul_f32_e32 v128, v129, v128
	v_mul_f32_e32 v122, v123, v122
	v_mul_f32_e32 v124, v125, v124
	v_add_f32_e32 v188, 1.0, v188
	v_add_f32_e32 v189, 1.0, v189
	v_add_f32_e32 v190, 1.0, v190
	v_add_f32_e32 v191, 1.0, v191
	v_cvt_pk_bf16_f32 v126, v126, v128
	v_cvt_pk_bf16_f32 v127, v122, v124
	v_mov_b32_e32 v192, v194
	global_store_dwordx2 v192, v[126:127], s[20:21]
	v_rcp_f32_e32 v188, v188
	v_rcp_f32_e32 v189, v189
	v_rcp_f32_e32 v190, v190
	v_rcp_f32_e32 v191, v191
	v_mul_f32_e32 v184, 0xbfb8aa3b, v110
	v_mul_f32_e32 v185, 0xbfb8aa3b, v112
	v_mul_f32_e32 v186, 0xbfb8aa3b, v106
	v_mul_f32_e32 v187, 0xbfb8aa3b, v108
	v_mul_f32_e32 v118, v118, v188
	v_mul_f32_e32 v120, v120, v189
	v_mul_f32_e32 v114, v114, v190
	v_mul_f32_e32 v116, v116, v191
	v_exp_f32_e32 v184, v184
	v_exp_f32_e32 v185, v185
	v_exp_f32_e32 v186, v186
	v_exp_f32_e32 v187, v187
	v_mul_f32_e32 v118, v119, v118
	v_mul_f32_e32 v120, v121, v120
	v_mul_f32_e32 v114, v115, v114
	v_mul_f32_e32 v116, v117, v116
	v_add_f32_e32 v184, 1.0, v184
	v_add_f32_e32 v185, 1.0, v185
	v_add_f32_e32 v186, 1.0, v186
	v_add_f32_e32 v187, 1.0, v187
	v_cvt_pk_bf16_f32 v118, v118, v120
	v_cvt_pk_bf16_f32 v119, v114, v116
	v_add_u32_e32 v193, 0x208000, v194
	global_store_dwordx2 v193, v[118:119], s[20:21]
	v_rcp_f32_e32 v184, v184
	v_rcp_f32_e32 v185, v185
	v_rcp_f32_e32 v186, v186
	v_rcp_f32_e32 v187, v187
	v_mul_f32_e32 v188, 0xbfb8aa3b, v102
	v_mul_f32_e32 v189, 0xbfb8aa3b, v104
	v_mul_f32_e32 v190, 0xbfb8aa3b, v98
	v_mul_f32_e32 v191, 0xbfb8aa3b, v100
	v_mul_f32_e32 v110, v110, v184
	v_mul_f32_e32 v112, v112, v185
	v_mul_f32_e32 v106, v106, v186
	v_mul_f32_e32 v108, v108, v187
	v_exp_f32_e32 v188, v188
	v_exp_f32_e32 v189, v189
	v_exp_f32_e32 v190, v190
	v_exp_f32_e32 v191, v191
	v_mul_f32_e32 v110, v111, v110
	v_mul_f32_e32 v112, v113, v112
	v_mul_f32_e32 v106, v107, v106
	v_mul_f32_e32 v108, v109, v108
	v_add_f32_e32 v188, 1.0, v188
	v_add_f32_e32 v189, 1.0, v189
	v_add_f32_e32 v190, 1.0, v190
	v_add_f32_e32 v191, 1.0, v191
	v_cvt_pk_bf16_f32 v110, v110, v112
	v_cvt_pk_bf16_f32 v111, v106, v108
	v_mov_b32_e32 v192, v194
	global_store_dwordx2 v192, v[110:111], s[20:21] offset:2048
	v_rcp_f32_e32 v188, v188
	v_rcp_f32_e32 v189, v189
	v_rcp_f32_e32 v190, v190
	v_rcp_f32_e32 v191, v191
	v_mul_f32_e32 v184, 0xbfb8aa3b, v94
	v_mul_f32_e32 v185, 0xbfb8aa3b, v96
	v_mul_f32_e32 v186, 0xbfb8aa3b, v90
	v_mul_f32_e32 v187, 0xbfb8aa3b, v92
	v_mul_f32_e32 v102, v102, v188
	v_mul_f32_e32 v104, v104, v189
	v_mul_f32_e32 v98, v98, v190
	v_mul_f32_e32 v100, v100, v191
	v_exp_f32_e32 v184, v184
	v_exp_f32_e32 v185, v185
	v_exp_f32_e32 v186, v186
	v_exp_f32_e32 v187, v187
	v_mul_f32_e32 v102, v103, v102
	v_mul_f32_e32 v104, v105, v104
	v_mul_f32_e32 v98, v99, v98
	v_mul_f32_e32 v100, v101, v100
	v_add_f32_e32 v184, 1.0, v184
	v_add_f32_e32 v185, 1.0, v185
	v_add_f32_e32 v186, 1.0, v186
	v_add_f32_e32 v187, 1.0, v187
	v_cvt_pk_bf16_f32 v102, v102, v104
	v_cvt_pk_bf16_f32 v103, v98, v100
	v_add_u32_e32 v193, 0x208000, v194
	global_store_dwordx2 v193, v[102:103], s[20:21] offset:2048
	v_rcp_f32_e32 v184, v184
	v_rcp_f32_e32 v185, v185
	v_rcp_f32_e32 v186, v186
	v_rcp_f32_e32 v187, v187
	v_mul_f32_e32 v188, 0xbfb8aa3b, v86
	v_mul_f32_e32 v189, 0xbfb8aa3b, v88
	v_mul_f32_e32 v190, 0xbfb8aa3b, v82
	v_mul_f32_e32 v191, 0xbfb8aa3b, v84
	v_mul_f32_e32 v94, v94, v184
	v_mul_f32_e32 v96, v96, v185
	v_mul_f32_e32 v90, v90, v186
	v_mul_f32_e32 v92, v92, v187
	v_exp_f32_e32 v188, v188
	v_exp_f32_e32 v189, v189
	v_exp_f32_e32 v190, v190
	v_exp_f32_e32 v191, v191
	v_mul_f32_e32 v94, v95, v94
	v_mul_f32_e32 v96, v97, v96
	v_mul_f32_e32 v90, v91, v90
	v_mul_f32_e32 v92, v93, v92
	v_add_f32_e32 v188, 1.0, v188
	v_add_f32_e32 v189, 1.0, v189
	v_add_f32_e32 v190, 1.0, v190
	v_add_f32_e32 v191, 1.0, v191
	v_cvt_pk_bf16_f32 v94, v94, v96
	v_cvt_pk_bf16_f32 v95, v90, v92
	v_add_u32_e32 v192, 0x1000, v194
	global_store_dwordx2 v192, v[94:95], s[20:21]
	v_rcp_f32_e32 v188, v188
	v_rcp_f32_e32 v189, v189
	v_rcp_f32_e32 v190, v190
	v_rcp_f32_e32 v191, v191
	v_mul_f32_e32 v184, 0xbfb8aa3b, v78
	v_mul_f32_e32 v185, 0xbfb8aa3b, v80
	v_mul_f32_e32 v186, 0xbfb8aa3b, v74
	v_mul_f32_e32 v187, 0xbfb8aa3b, v76
	v_mul_f32_e32 v86, v86, v188
	v_mul_f32_e32 v88, v88, v189
	v_mul_f32_e32 v82, v82, v190
	v_mul_f32_e32 v84, v84, v191
	v_exp_f32_e32 v184, v184
	v_exp_f32_e32 v185, v185
	v_exp_f32_e32 v186, v186
; DI unsigned cvt_pk_bf16(float lo, float hi) { unsigned r; asm volatile("v_cvt_pk_bf16_f32 %0, %1, %2" : "=v"(r) : "v"(lo), "v"(hi)); return r; }
; DI float sigmoidf_(float x) { return __builtin_amdgcn_rcpf(1.f + __expf(-x)); }
;     DI void operator()(const Acc& acc, const Unit& u, int wr, int wc, int fr, int fq) const {
;     ...
;             for (int m = 0; m < 4; ++m) { const int row = u.pm * 256 + ai * 128 + wr * 64 + m * 16 + fr;
; #pragma unroll
;                 for (int bj = 0; bj < 2; ++bj) { const int j0 = u.pn * 128 + bj * 64 + wc * 16 + 4 * fq; const f32x4 v0 = acc[ai][bj][m][0], v1 = acc[ai][bj][m][1];
;                     const float h0 = v0[0] * sigmoidf_(v0[0]) * v0[1], h1 = v0[2] * sigmoidf_(v0[2]) * v0[3], h2 = v1[0] * sigmoidf_(v1[0]) * v1[1], h3 = v1[2] * sigmoidf_(v1[2]) * v1[3];
;                     u32x2 w; w.x = cvt_pk_bf16(h0, h1); w.y = cvt_pk_bf16(h2, h3);
;                     *(u32x2*)(H + (size_t)(j0 >> 6) * NT * 64 + (size_t)row * 64 + (j0 & 63)) = w; }
;                 asm volatile("" ::: "memory"); }
	v_exp_f32_e32 v187, v187
	v_mul_f32_e32 v86, v87, v86
	v_mul_f32_e32 v88, v89, v88
	v_mul_f32_e32 v82, v83, v82
	v_mul_f32_e32 v84, v85, v84
	v_add_f32_e32 v184, 1.0, v184
	v_add_f32_e32 v185, 1.0, v185
	v_add_f32_e32 v186, 1.0, v186
	v_add_f32_e32 v187, 1.0, v187
	v_cvt_pk_bf16_f32 v86, v86, v88
	v_cvt_pk_bf16_f32 v87, v82, v84
	v_add_u32_e32 v193, 0x209000, v194
	global_store_dwordx2 v193, v[86:87], s[20:21]
	v_rcp_f32_e32 v184, v184
	v_rcp_f32_e32 v185, v185
	v_rcp_f32_e32 v186, v186
	v_rcp_f32_e32 v187, v187
	v_mul_f32_e32 v188, 0xbfb8aa3b, v70
	v_mul_f32_e32 v189, 0xbfb8aa3b, v72
	v_mul_f32_e32 v190, 0xbfb8aa3b, v66
	v_mul_f32_e32 v191, 0xbfb8aa3b, v68
	v_mul_f32_e32 v78, v78, v184
	v_mul_f32_e32 v80, v80, v185
	v_mul_f32_e32 v74, v74, v186
	v_mul_f32_e32 v76, v76, v187
	v_exp_f32_e32 v188, v188
	v_exp_f32_e32 v189, v189
	v_exp_f32_e32 v190, v190
	v_exp_f32_e32 v191, v191
	v_mul_f32_e32 v78, v79, v78
	v_mul_f32_e32 v80, v81, v80
	v_mul_f32_e32 v74, v75, v74
	v_mul_f32_e32 v76, v77, v76
	v_add_f32_e32 v188, 1.0, v188
	v_add_f32_e32 v189, 1.0, v189
	v_add_f32_e32 v190, 1.0, v190
	v_add_f32_e32 v191, 1.0, v191
	v_cvt_pk_bf16_f32 v78, v78, v80
	v_cvt_pk_bf16_f32 v79, v74, v76
	v_add_u32_e32 v192, 0x1000, v194
	global_store_dwordx2 v192, v[78:79], s[20:21] offset:2048
	v_rcp_f32_e32 v188, v188
	v_rcp_f32_e32 v189, v189
	v_rcp_f32_e32 v190, v190
	v_rcp_f32_e32 v191, v191
	v_mul_f32_e32 v184, 0xbfb8aa3b, v62
	v_mul_f32_e32 v185, 0xbfb8aa3b, v64
	v_mul_f32_e32 v186, 0xbfb8aa3b, v58
	v_mul_f32_e32 v187, 0xbfb8aa3b, v60
	v_mul_f32_e32 v70, v70, v188
	v_mul_f32_e32 v72, v72, v189
	v_mul_f32_e32 v66, v66, v190
	v_mul_f32_e32 v68, v68, v191
	v_exp_f32_e32 v184, v184
	v_exp_f32_e32 v185, v185
	v_exp_f32_e32 v186, v186
	v_exp_f32_e32 v187, v187
	v_mul_f32_e32 v70, v71, v70
	v_mul_f32_e32 v72, v73, v72
	v_mul_f32_e32 v66, v67, v66
	v_mul_f32_e32 v68, v69, v68
	v_add_f32_e32 v184, 1.0, v184
	v_add_f32_e32 v185, 1.0, v185
	v_add_f32_e32 v186, 1.0, v186
	v_add_f32_e32 v187, 1.0, v187
	v_cvt_pk_bf16_f32 v70, v70, v72
	v_cvt_pk_bf16_f32 v71, v66, v68
	v_add_u32_e32 v193, 0x209000, v194
	global_store_dwordx2 v193, v[70:71], s[20:21] offset:2048
	v_rcp_f32_e32 v184, v184
	v_rcp_f32_e32 v185, v185
	v_rcp_f32_e32 v186, v186
	v_rcp_f32_e32 v187, v187
	v_mul_f32_e32 v188, 0xbfb8aa3b, v54
	v_mul_f32_e32 v189, 0xbfb8aa3b, v56
	v_mul_f32_e32 v190, 0xbfb8aa3b, v50
	v_mul_f32_e32 v191, 0xbfb8aa3b, v52
	v_mul_f32_e32 v62, v62, v184
	v_mul_f32_e32 v64, v64, v185
	v_mul_f32_e32 v58, v58, v186
	v_mul_f32_e32 v60, v60, v187
	v_exp_f32_e32 v188, v188
	v_exp_f32_e32 v189, v189
	v_exp_f32_e32 v190, v190
	v_exp_f32_e32 v191, v191
	v_mul_f32_e32 v62, v63, v62
	v_mul_f32_e32 v64, v65, v64
	v_mul_f32_e32 v58, v59, v58
	v_mul_f32_e32 v60, v61, v60
	v_add_f32_e32 v188, 1.0, v188
	v_add_f32_e32 v189, 1.0, v189
	v_add_f32_e32 v190, 1.0, v190
	v_add_f32_e32 v191, 1.0, v191
	v_cvt_pk_bf16_f32 v62, v62, v64
	v_cvt_pk_bf16_f32 v63, v58, v60
	v_add_u32_e32 v192, 0x4000, v194
	global_store_dwordx2 v192, v[62:63], s[20:21]
	v_rcp_f32_e32 v188, v188
	v_rcp_f32_e32 v189, v189
	v_rcp_f32_e32 v190, v190
	v_rcp_f32_e32 v191, v191
	v_mul_f32_e32 v184, 0xbfb8aa3b, v46
	v_mul_f32_e32 v185, 0xbfb8aa3b, v48
	v_mul_f32_e32 v186, 0xbfb8aa3b, v42
	v_mul_f32_e32 v187, 0xbfb8aa3b, v44
	v_mul_f32_e32 v54, v54, v188
	v_mul_f32_e32 v56, v56, v189
	v_mul_f32_e32 v50, v50, v190
	v_mul_f32_e32 v52, v52, v191
	v_exp_f32_e32 v184, v184
	v_exp_f32_e32 v185, v185
	v_exp_f32_e32 v186, v186
	v_exp_f32_e32 v187, v187
	v_mul_f32_e32 v54, v55, v54
	v_mul_f32_e32 v56, v57, v56
	v_mul_f32_e32 v50, v51, v50
	v_mul_f32_e32 v52, v53, v52
	v_add_f32_e32 v184, 1.0, v184
	v_add_f32_e32 v185, 1.0, v185
	v_add_f32_e32 v186, 1.0, v186
	v_add_f32_e32 v187, 1.0, v187
	v_cvt_pk_bf16_f32 v54, v54, v56
	v_cvt_pk_bf16_f32 v55, v50, v52
	v_add_u32_e32 v193, 0x20c000, v194
	global_store_dwordx2 v193, v[54:55], s[20:21]
	v_rcp_f32_e32 v184, v184
	v_rcp_f32_e32 v185, v185
	v_rcp_f32_e32 v186, v186
	v_rcp_f32_e32 v187, v187
	v_mul_f32_e32 v188, 0xbfb8aa3b, v38
	v_mul_f32_e32 v189, 0xbfb8aa3b, v40
	v_mul_f32_e32 v190, 0xbfb8aa3b, v34
	v_mul_f32_e32 v191, 0xbfb8aa3b, v36
	v_mul_f32_e32 v46, v46, v184
	v_mul_f32_e32 v48, v48, v185
	v_mul_f32_e32 v42, v42, v186
	v_mul_f32_e32 v44, v44, v187
	v_exp_f32_e32 v188, v188
	v_exp_f32_e32 v189, v189
	v_exp_f32_e32 v190, v190
	v_exp_f32_e32 v191, v191
	v_mul_f32_e32 v46, v47, v46
	v_mul_f32_e32 v48, v49, v48
	v_mul_f32_e32 v42, v43, v42
; DI unsigned cvt_pk_bf16(float lo, float hi) { unsigned r; asm volatile("v_cvt_pk_bf16_f32 %0, %1, %2" : "=v"(r) : "v"(lo), "v"(hi)); return r; }
; DI float sigmoidf_(float x) { return __builtin_amdgcn_rcpf(1.f + __expf(-x)); }
; #define PG8_BAR __builtin_amdgcn_s_barrier()
; template <class Epi>
; DI void gemm_phase(LAS unsigned char* lds, const Gemm g, const StaticOrder& S, const Epi& E) {
;     ...
;         if (!has_next) break;
; #pragma unroll
;         for (int a = 0; a < 2; ++a)
; #pragma unroll
;             for (int b = 0; b < 2; ++b)
; #pragma unroll
;                 for (int m = 0; m < 4; ++m)
; #pragma unroll
;                     for (int n = 0; n < 2; ++n) acc[a][b][m][n] = (f32x4){0.f, 0.f, 0.f, 0.f};
;         cur = nxt; cA = nA; cB = nB; ++ui;
;         if (wr == 1) PG8_BAR;
;     DI void operator()(const Acc& acc, const Unit& u, int wr, int wc, int fr, int fq) const {
;     ...
;             for (int m = 0; m < 4; ++m) { const int row = u.pm * 256 + ai * 128 + wr * 64 + m * 16 + fr;
; #pragma unroll
;                 for (int bj = 0; bj < 2; ++bj) { const int j0 = u.pn * 128 + bj * 64 + wc * 16 + 4 * fq; const f32x4 v0 = acc[ai][bj][m][0], v1 = acc[ai][bj][m][1];
;                     const float h0 = v0[0] * sigmoidf_(v0[0]) * v0[1], h1 = v0[2] * sigmoidf_(v0[2]) * v0[3], h2 = v1[0] * sigmoidf_(v1[0]) * v1[1], h3 = v1[2] * sigmoidf_(v1[2]) * v1[3];
;                     u32x2 w; w.x = cvt_pk_bf16(h0, h1); w.y = cvt_pk_bf16(h2, h3);
;                     *(u32x2*)(H + (size_t)(j0 >> 6) * NT * 64 + (size_t)row * 64 + (j0 & 63)) = w; }
;                 asm volatile("" ::: "memory"); }
	v_mul_f32_e32 v44, v45, v44
	v_add_f32_e32 v188, 1.0, v188
	v_add_f32_e32 v189, 1.0, v189
	v_add_f32_e32 v190, 1.0, v190
	v_add_f32_e32 v191, 1.0, v191
	v_cvt_pk_bf16_f32 v46, v46, v48
	v_cvt_pk_bf16_f32 v47, v42, v44
	v_add_u32_e32 v192, 0x4000, v194
	global_store_dwordx2 v192, v[46:47], s[20:21] offset:2048
	v_rcp_f32_e32 v188, v188
	v_rcp_f32_e32 v189, v189
	v_rcp_f32_e32 v190, v190
	v_rcp_f32_e32 v191, v191
	v_mul_f32_e32 v184, 0xbfb8aa3b, v30
	v_mul_f32_e32 v185, 0xbfb8aa3b, v32
	v_mul_f32_e32 v186, 0xbfb8aa3b, v26
	v_mul_f32_e32 v187, 0xbfb8aa3b, v28
	v_mul_f32_e32 v38, v38, v188
	v_mul_f32_e32 v40, v40, v189
	v_mul_f32_e32 v34, v34, v190
	v_mul_f32_e32 v36, v36, v191
	v_exp_f32_e32 v184, v184
	v_exp_f32_e32 v185, v185
	v_exp_f32_e32 v186, v186
	v_exp_f32_e32 v187, v187
	v_mul_f32_e32 v38, v39, v38
	v_mul_f32_e32 v40, v41, v40
	v_mul_f32_e32 v34, v35, v34
	v_mul_f32_e32 v36, v37, v36
	v_add_f32_e32 v184, 1.0, v184
	v_add_f32_e32 v185, 1.0, v185
	v_add_f32_e32 v186, 1.0, v186
	v_add_f32_e32 v187, 1.0, v187
	v_cvt_pk_bf16_f32 v38, v38, v40
	v_cvt_pk_bf16_f32 v39, v34, v36
	v_add_u32_e32 v193, 0x20c000, v194
	global_store_dwordx2 v193, v[38:39], s[20:21] offset:2048
	v_rcp_f32_e32 v184, v184
	v_rcp_f32_e32 v185, v185
	v_rcp_f32_e32 v186, v186
	v_rcp_f32_e32 v187, v187
	v_mul_f32_e32 v188, 0xbfb8aa3b, v22
	v_mul_f32_e32 v189, 0xbfb8aa3b, v24
	v_mul_f32_e32 v190, 0xbfb8aa3b, v18
	v_mul_f32_e32 v191, 0xbfb8aa3b, v20
	v_mul_f32_e32 v30, v30, v184
	v_mul_f32_e32 v32, v32, v185
	v_mul_f32_e32 v26, v26, v186
	v_mul_f32_e32 v28, v28, v187
	v_exp_f32_e32 v188, v188
	v_exp_f32_e32 v189, v189
	v_exp_f32_e32 v190, v190
	v_exp_f32_e32 v191, v191
	v_mul_f32_e32 v30, v31, v30
	v_mul_f32_e32 v32, v33, v32
	v_mul_f32_e32 v26, v27, v26
	v_mul_f32_e32 v28, v29, v28
	v_add_f32_e32 v188, 1.0, v188
	v_add_f32_e32 v189, 1.0, v189
	v_add_f32_e32 v190, 1.0, v190
	v_add_f32_e32 v191, 1.0, v191
	v_cvt_pk_bf16_f32 v30, v30, v32
	v_cvt_pk_bf16_f32 v31, v26, v28
	v_add_u32_e32 v192, 0x5000, v194
	global_store_dwordx2 v192, v[30:31], s[20:21]
	v_rcp_f32_e32 v188, v188
	v_rcp_f32_e32 v189, v189
	v_rcp_f32_e32 v190, v190
	v_rcp_f32_e32 v191, v191
	v_mul_f32_e32 v184, 0xbfb8aa3b, v14
	v_mul_f32_e32 v185, 0xbfb8aa3b, v16
	v_mul_f32_e32 v186, 0xbfb8aa3b, v10
	v_mul_f32_e32 v187, 0xbfb8aa3b, v12
	v_mul_f32_e32 v22, v22, v188
	v_mul_f32_e32 v24, v24, v189
	v_mul_f32_e32 v18, v18, v190
	v_mul_f32_e32 v20, v20, v191
	v_exp_f32_e32 v184, v184
	v_exp_f32_e32 v185, v185
	v_exp_f32_e32 v186, v186
	v_exp_f32_e32 v187, v187
	v_mul_f32_e32 v22, v23, v22
	v_mul_f32_e32 v24, v25, v24
	v_mul_f32_e32 v18, v19, v18
	v_mul_f32_e32 v20, v21, v20
	v_add_f32_e32 v184, 1.0, v184
	v_add_f32_e32 v185, 1.0, v185
	v_add_f32_e32 v186, 1.0, v186
	v_add_f32_e32 v187, 1.0, v187
	v_cvt_pk_bf16_f32 v22, v22, v24
	v_cvt_pk_bf16_f32 v23, v18, v20
	v_add_u32_e32 v193, 0x20d000, v194
	global_store_dwordx2 v193, v[22:23], s[20:21]
	v_rcp_f32_e32 v184, v184
	v_rcp_f32_e32 v185, v185
	v_rcp_f32_e32 v186, v186
	v_rcp_f32_e32 v187, v187
	v_mul_f32_e32 v188, 0xbfb8aa3b, v6
	v_mul_f32_e32 v189, 0xbfb8aa3b, v8
	v_mul_f32_e32 v190, 0xbfb8aa3b, v2
	v_mul_f32_e32 v191, 0xbfb8aa3b, v4
	v_mul_f32_e32 v14, v14, v184
	v_mul_f32_e32 v16, v16, v185
	v_mul_f32_e32 v10, v10, v186
	v_mul_f32_e32 v12, v12, v187
	v_exp_f32_e32 v188, v188
	v_exp_f32_e32 v189, v189
	v_exp_f32_e32 v190, v190
	v_exp_f32_e32 v191, v191
	v_mul_f32_e32 v14, v15, v14
	v_mul_f32_e32 v16, v17, v16
	v_mul_f32_e32 v10, v11, v10
	v_mul_f32_e32 v12, v13, v12
	v_add_f32_e32 v188, 1.0, v188
	v_add_f32_e32 v189, 1.0, v189
	v_add_f32_e32 v190, 1.0, v190
	v_add_f32_e32 v191, 1.0, v191
	v_cvt_pk_bf16_f32 v14, v14, v16
	v_cvt_pk_bf16_f32 v15, v10, v12
	v_add_u32_e32 v192, 0x5000, v194
	global_store_dwordx2 v192, v[14:15], s[20:21] offset:2048
	v_rcp_f32_e32 v188, v188
	v_rcp_f32_e32 v189, v189
	v_rcp_f32_e32 v190, v190
	v_rcp_f32_e32 v191, v191
	s_nop 0
	v_mul_f32_e32 v6, v6, v188
	v_mul_f32_e32 v8, v8, v189
	v_mul_f32_e32 v2, v2, v190
	v_mul_f32_e32 v4, v4, v191
	v_mul_f32_e32 v6, v7, v6
	v_mul_f32_e32 v8, v9, v8
	v_mul_f32_e32 v2, v3, v2
	v_mul_f32_e32 v4, v5, v4
	v_cvt_pk_bf16_f32 v6, v6, v8
	v_cvt_pk_bf16_f32 v7, v2, v4
	v_add_u32_e32 v193, 0x20d000, v194
	global_store_dwordx2 v193, v[6:7], s[20:21] offset:2048
	s_mov_b64 s[18:19], -1
	s_andn2_b64 vcc, exec, s[40:41]
	s_cbranch_vccnz .LBB0_2154
	s_andn2_b64 vcc, exec, s[0:1]
	s_cbranch_vccnz .LBB0_2153
	s_barrier
	s_branch .LBB0_2153
